# P2 rebalancing: kmean items assigned as wave*grid+block (waves 0-3 of every workgroup) instead of block*8+wave (all waves of half the workgroups); on top of v60
# speedup vs baseline: 1.0018x; 1.0018x over previous
.LBB0_698:
	s_or_b64 exec, exec, s[6:7]
	s_load_dword s2, s[90:91], 0x110
	s_waitcnt lgkmcnt(0)
	s_mul_i32 s3, s93, s2
	s_add_i32 s3, s3, s94
	s_cmpk_gt_i32 s3, 0x3ff
	s_cbranch_scc1 .LBB0_703
	v_lshlrev_b32_e32 v0, 4, v148
	v_mov_b32_e32 v1, 0
	v_lshl_add_u64 v[2:3], s[86:87], 0, v[0:1]
	v_mbcnt_lo_u32_b32 v0, -1, 0
	s_mov_b64 s[4:5], 0xc800000
	v_mbcnt_hi_u32_b32 v0, -1, v0
	v_lshl_add_u64 v[108:109], v[2:3], 0, s[4:5]
	v_and_b32_e32 v3, 64, v0
	v_xor_b32_e32 v2, 8, v0
	v_add_u32_e32 v3, 64, v3
	v_cmp_lt_i32_e32 vcc, v2, v3
	s_mov_b64 s[4:5], 0x2700000
	s_waitcnt lgkmcnt(0)
	s_lshl_b32 s9, s2, 3
	v_cndmask_b32_e32 v2, v0, v2, vcc
	v_lshlrev_b32_e32 v112, 2, v2
	v_xor_b32_e32 v2, 16, v0
	v_cmp_lt_i32_e32 vcc, v2, v3
	v_cmp_gt_u32_e64 s[6:7], 8, v148
	s_movk_i32 s12, 0x1000
	v_cndmask_b32_e32 v2, v0, v2, vcc
	v_lshlrev_b32_e32 v113, 2, v2
	v_xor_b32_e32 v2, 32, v0
	v_cmp_lt_i32_e32 vcc, v2, v3
	s_movk_i32 s13, 0x2000
	s_movk_i32 s14, 0x3000
	v_cndmask_b32_e32 v0, v0, v2, vcc
	v_lshlrev_b32_e32 v114, 2, v0
	v_lshlrev_b32_e32 v0, 5, v148
	v_lshl_add_u64 v[0:1], s[86:87], 0, v[0:1]
	v_lshl_add_u64 v[110:111], v[0:1], 0, s[4:5]
	s_movk_i32 s15, 0x4000
	s_movk_i32 s16, 0x5000
	s_movk_i32 s17, 0x6000
	s_movk_i32 s20, 0x7000
	s_mov_b32 s8, 0x3b800000
	s_branch .LBB0_701
